# v99 + converter workgroups rate-limited during GEMM1 (s_sleep 36 per weight item)
# baseline (speedup 1.0000x reference)
.LBB0_80:
	s_cmp_lg_u32 s101, 2
	s_cbranch_scc1 .Lp0_nothr
	s_sleep 36
